# zig-zag MFMA order + in-proj m=3 A-fragment tuples moved to bank-0-aligned free VGPRs (v224-v231)
# speedup vs baseline: 1.0147x; 1.0015x over previous
.LBB0_127:
	s_add_u32 s2, s0, 0xfff80080
	s_addc_u32 s3, s1, -1
	s_add_i32 s50, 0, 0x10000
	s_cmp_eq_u32 s49, 28
	s_cselect_b32 s5, s23, s3
	s_cselect_b32 s4, s27, s2
	s_cselect_b32 s3, s9, s48
	s_cselect_b32 s2, s46, s47
	s_add_i32 s52, 0, 0x14000
	v_add_u32_e32 v154, s50, v163
	v_add_u32_e32 v176, s52, v163
	ds_read_b128 v[142:145], v154
	ds_read_b128 v[146:149], v154 offset:1024
	ds_read_b128 v[150:153], v154 offset:2048
	ds_read_b128 v[154:157], v154 offset:3072
	ds_read_b128 v[158:161], v176
	ds_read_b128 v[168:171], v176 offset:1024
	ds_read_b128 v[172:175], v176 offset:2048
	ds_read_b128 v[176:179], v176 offset:3072
	v_lshl_add_u64 v[204:205], s[0:1], 0, v[138:139]
	s_add_i32 m0, s11, 0xc000
	ds_read_b128 v[180:183], v167
	ds_read_b128 v[184:187], v167 offset:1024
	ds_read_b128 v[188:191], v167 offset:2048
	ds_read_b128 v[192:195], v167 offset:3072
	ds_read_b128 v[196:199], v167 offset:4096
	ds_read_b128 v[200:203], v167 offset:5120
	ds_read_b128 v[224:227], v167 offset:6144
	ds_read_b128 v[228:231], v167 offset:7168
	global_load_lds_dwordx4 v[204:205], off
	v_lshl_add_u64 v[204:205], s[0:1], 0, v[140:141]
	s_add_i32 m0, s11, 0xe000
	s_nop 0
	global_load_lds_dwordx4 v[204:205], off
	s_waitcnt vmcnt(8)
	s_waitcnt lgkmcnt(0)
	s_barrier
	s_setprio 1
	s_waitcnt lgkmcnt(0)
	v_mfma_f32_16x16x32_bf16 v[126:129], v[142:145], v[180:183], v[126:129]
	v_mfma_f32_16x16x32_bf16 v[126:129], v[146:149], v[184:187], v[126:129]
	v_mfma_f32_16x16x32_bf16 v[122:125], v[154:157], v[184:187], v[122:125]
	v_mfma_f32_16x16x32_bf16 v[122:125], v[150:153], v[180:183], v[122:125]
	v_mfma_f32_16x16x32_bf16 v[106:109], v[150:153], v[188:191], v[106:109]
	v_mfma_f32_16x16x32_bf16 v[106:109], v[154:157], v[192:195], v[106:109]
	v_mfma_f32_16x16x32_bf16 v[110:113], v[146:149], v[192:195], v[110:113]
	v_mfma_f32_16x16x32_bf16 v[110:113], v[142:145], v[188:191], v[110:113]
	v_mfma_f32_16x16x32_bf16 v[94:97], v[142:145], v[196:199], v[94:97]
	v_mfma_f32_16x16x32_bf16 v[94:97], v[146:149], v[200:203], v[94:97]
	v_mfma_f32_16x16x32_bf16 v[90:93], v[154:157], v[200:203], v[90:93]
	v_mfma_f32_16x16x32_bf16 v[90:93], v[150:153], v[196:199], v[90:93]
	v_mfma_f32_16x16x32_bf16 v[74:77], v[150:153], v[224:227], v[74:77]
	v_mfma_f32_16x16x32_bf16 v[74:77], v[154:157], v[228:231], v[74:77]
	v_mfma_f32_16x16x32_bf16 v[78:81], v[146:149], v[228:231], v[78:81]
	v_mfma_f32_16x16x32_bf16 v[78:81], v[142:145], v[224:227], v[78:81]
	s_setprio 0
	s_setprio 1
	v_mfma_f32_16x16x32_bf16 v[118:121], v[158:161], v[180:183], v[118:121]
	v_mfma_f32_16x16x32_bf16 v[118:121], v[168:171], v[184:187], v[118:121]
	v_mfma_f32_16x16x32_bf16 v[114:117], v[176:179], v[184:187], v[114:117]
	v_mfma_f32_16x16x32_bf16 v[114:117], v[172:175], v[180:183], v[114:117]
	v_mfma_f32_16x16x32_bf16 v[98:101], v[172:175], v[188:191], v[98:101]
	v_mfma_f32_16x16x32_bf16 v[98:101], v[176:179], v[192:195], v[98:101]
	v_mfma_f32_16x16x32_bf16 v[102:105], v[168:171], v[192:195], v[102:105]
	v_mfma_f32_16x16x32_bf16 v[102:105], v[158:161], v[188:191], v[102:105]
	v_mfma_f32_16x16x32_bf16 v[86:89], v[158:161], v[196:199], v[86:89]
	v_mfma_f32_16x16x32_bf16 v[86:89], v[168:171], v[200:203], v[86:89]
	v_mfma_f32_16x16x32_bf16 v[82:85], v[176:179], v[200:203], v[82:85]
	v_mfma_f32_16x16x32_bf16 v[82:85], v[172:175], v[196:199], v[82:85]
	v_mfma_f32_16x16x32_bf16 v[66:69], v[172:175], v[224:227], v[66:69]
	v_mfma_f32_16x16x32_bf16 v[66:69], v[176:179], v[228:231], v[66:69]
	v_mfma_f32_16x16x32_bf16 v[70:73], v[168:171], v[228:231], v[70:73]
	v_mfma_f32_16x16x32_bf16 v[70:73], v[158:161], v[224:227], v[70:73]
	s_setprio 0
	s_barrier
	s_add_i32 s50, s50, s31
	v_lshl_add_u64 v[204:205], s[2:3], 0, v[0:1]
	s_mov_b32 m0, s50
	ds_read_b128 v[180:183], v167 offset:16384
	ds_read_b128 v[184:187], v167 offset:17408
	ds_read_b128 v[188:191], v167 offset:18432
	ds_read_b128 v[192:195], v167 offset:19456
	ds_read_b128 v[196:199], v167 offset:20480
	ds_read_b128 v[200:203], v167 offset:21504
	ds_read_b128 v[224:227], v167 offset:22528
	ds_read_b128 v[228:231], v167 offset:23552
	global_load_lds_dwordx4 v[204:205], off
	s_add_i32 m0, s50, 0x2000
	s_add_u32 s50, s2, 0x80000
	v_lshl_add_u64 v[206:207], s[2:3], 0, v[134:135]
	s_addc_u32 s51, s3, 0
	s_add_i32 s52, s52, s31
	global_load_lds_dwordx4 v[206:207], off
	v_lshl_add_u64 v[218:219], s[50:51], 0, v[0:1]
	s_mov_b32 m0, s52
	v_lshl_add_u64 v[220:221], s[4:5], 0, v[132:133]
	global_load_lds_dwordx4 v[218:219], off
	v_lshl_add_u64 v[218:219], s[50:51], 0, v[134:135]
	s_add_i32 m0, s52, 0x2000
	s_nop 0
	global_load_lds_dwordx4 v[218:219], off
	v_lshl_add_u64 v[218:219], s[4:5], 0, v[130:131]
	s_mov_b32 m0, s11
	s_nop 0
	global_load_lds_dwordx4 v[218:219], off
	s_mov_b32 m0, s35
	s_nop 0
	global_load_lds_dwordx4 v[220:221], off
	s_waitcnt vmcnt(8)
	s_waitcnt lgkmcnt(0)
	s_barrier
	s_setprio 1
	s_waitcnt lgkmcnt(0)
	v_mfma_f32_16x16x32_bf16 v[62:65], v[142:145], v[180:183], v[62:65]
	v_mfma_f32_16x16x32_bf16 v[62:65], v[146:149], v[184:187], v[62:65]
	v_mfma_f32_16x16x32_bf16 v[58:61], v[154:157], v[184:187], v[58:61]
	v_mfma_f32_16x16x32_bf16 v[58:61], v[150:153], v[180:183], v[58:61]
	v_mfma_f32_16x16x32_bf16 v[42:45], v[150:153], v[188:191], v[42:45]
	v_mfma_f32_16x16x32_bf16 v[42:45], v[154:157], v[192:195], v[42:45]
	v_mfma_f32_16x16x32_bf16 v[46:49], v[146:149], v[192:195], v[46:49]
	v_mfma_f32_16x16x32_bf16 v[46:49], v[142:145], v[188:191], v[46:49]
	v_mfma_f32_16x16x32_bf16 v[30:33], v[142:145], v[196:199], v[30:33]
	v_mfma_f32_16x16x32_bf16 v[30:33], v[146:149], v[200:203], v[30:33]
	v_mfma_f32_16x16x32_bf16 v[26:29], v[154:157], v[200:203], v[26:29]
	v_mfma_f32_16x16x32_bf16 v[26:29], v[150:153], v[196:199], v[26:29]
	v_mfma_f32_16x16x32_bf16 v[10:13], v[150:153], v[224:227], v[10:13]
	v_mfma_f32_16x16x32_bf16 v[10:13], v[154:157], v[228:231], v[10:13]
	v_mfma_f32_16x16x32_bf16 v[14:17], v[146:149], v[228:231], v[14:17]
	v_mfma_f32_16x16x32_bf16 v[14:17], v[142:145], v[224:227], v[14:17]
	s_setprio 0
	s_setprio 1
	v_mfma_f32_16x16x32_bf16 v[54:57], v[158:161], v[180:183], v[54:57]
	v_mfma_f32_16x16x32_bf16 v[54:57], v[168:171], v[184:187], v[54:57]
	v_mfma_f32_16x16x32_bf16 v[50:53], v[176:179], v[184:187], v[50:53]
	v_mfma_f32_16x16x32_bf16 v[50:53], v[172:175], v[180:183], v[50:53]
	v_mfma_f32_16x16x32_bf16 v[34:37], v[172:175], v[188:191], v[34:37]
	v_mfma_f32_16x16x32_bf16 v[34:37], v[176:179], v[192:195], v[34:37]
	v_mfma_f32_16x16x32_bf16 v[38:41], v[168:171], v[192:195], v[38:41]
	v_mfma_f32_16x16x32_bf16 v[38:41], v[158:161], v[188:191], v[38:41]
	v_mfma_f32_16x16x32_bf16 v[22:25], v[158:161], v[196:199], v[22:25]
	v_mfma_f32_16x16x32_bf16 v[22:25], v[168:171], v[200:203], v[22:25]
	v_mfma_f32_16x16x32_bf16 v[18:21], v[176:179], v[200:203], v[18:21]
	v_mfma_f32_16x16x32_bf16 v[18:21], v[172:175], v[196:199], v[18:21]
	v_mfma_f32_16x16x32_bf16 v[2:5], v[172:175], v[224:227], v[2:5]
	v_mfma_f32_16x16x32_bf16 v[2:5], v[176:179], v[228:231], v[2:5]
	v_mfma_f32_16x16x32_bf16 v[6:9], v[168:171], v[228:231], v[6:9]
	v_mfma_f32_16x16x32_bf16 v[6:9], v[158:161], v[224:227], v[6:9]
	s_setprio 0
	s_barrier
	s_add_i32 s50, 0, 0x18000
	s_add_i32 s51, 0, 0x1c000
	v_add_u32_e32 v154, s50, v163
	v_add_u32_e32 v176, s51, v163
	ds_read_b128 v[142:145], v154
	ds_read_b128 v[146:149], v154 offset:1024
	ds_read_b128 v[150:153], v154 offset:2048
	ds_read_b128 v[154:157], v154 offset:3072
	ds_read_b128 v[158:161], v176
	ds_read_b128 v[168:171], v176 offset:1024
	ds_read_b128 v[172:175], v176 offset:2048
	ds_read_b128 v[176:179], v176 offset:3072
	s_add_u32 s4, s4, 0x80000
	s_addc_u32 s5, s5, 0
	s_mov_b32 m0, s36
	v_lshl_add_u64 v[222:223], s[4:5], 0, v[130:131]
	ds_read_b128 v[180:183], v167 offset:32768
	ds_read_b128 v[184:187], v167 offset:33792
	ds_read_b128 v[188:191], v167 offset:34816
	ds_read_b128 v[192:195], v167 offset:35840
	ds_read_b128 v[196:199], v167 offset:36864
	ds_read_b128 v[200:203], v167 offset:37888
	ds_read_b128 v[224:227], v167 offset:38912
	ds_read_b128 v[228:231], v167 offset:39936
	global_load_lds_dwordx4 v[222:223], off
	v_lshl_add_u64 v[222:223], s[4:5], 0, v[132:133]
	s_mov_b32 m0, s37
	s_nop 0
	global_load_lds_dwordx4 v[222:223], off
	s_waitcnt vmcnt(8)
	s_waitcnt lgkmcnt(0)
	s_barrier
	s_setprio 1
	s_waitcnt lgkmcnt(0)
	v_mfma_f32_16x16x32_bf16 v[126:129], v[142:145], v[180:183], v[126:129]
	v_mfma_f32_16x16x32_bf16 v[126:129], v[146:149], v[184:187], v[126:129]
	v_mfma_f32_16x16x32_bf16 v[122:125], v[154:157], v[184:187], v[122:125]
	v_mfma_f32_16x16x32_bf16 v[122:125], v[150:153], v[180:183], v[122:125]
	v_mfma_f32_16x16x32_bf16 v[106:109], v[150:153], v[188:191], v[106:109]
	v_mfma_f32_16x16x32_bf16 v[106:109], v[154:157], v[192:195], v[106:109]
	v_mfma_f32_16x16x32_bf16 v[110:113], v[146:149], v[192:195], v[110:113]
	v_mfma_f32_16x16x32_bf16 v[110:113], v[142:145], v[188:191], v[110:113]
	v_mfma_f32_16x16x32_bf16 v[94:97], v[142:145], v[196:199], v[94:97]
	v_mfma_f32_16x16x32_bf16 v[94:97], v[146:149], v[200:203], v[94:97]
	v_mfma_f32_16x16x32_bf16 v[90:93], v[154:157], v[200:203], v[90:93]
	v_mfma_f32_16x16x32_bf16 v[90:93], v[150:153], v[196:199], v[90:93]
	v_mfma_f32_16x16x32_bf16 v[74:77], v[150:153], v[224:227], v[74:77]
	v_mfma_f32_16x16x32_bf16 v[74:77], v[154:157], v[228:231], v[74:77]
	v_mfma_f32_16x16x32_bf16 v[78:81], v[146:149], v[228:231], v[78:81]
	v_mfma_f32_16x16x32_bf16 v[78:81], v[142:145], v[224:227], v[78:81]
	s_setprio 0
	s_setprio 1
	v_mfma_f32_16x16x32_bf16 v[118:121], v[158:161], v[180:183], v[118:121]
	v_mfma_f32_16x16x32_bf16 v[118:121], v[168:171], v[184:187], v[118:121]
	v_mfma_f32_16x16x32_bf16 v[114:117], v[176:179], v[184:187], v[114:117]
	v_mfma_f32_16x16x32_bf16 v[114:117], v[172:175], v[180:183], v[114:117]
	v_mfma_f32_16x16x32_bf16 v[98:101], v[172:175], v[188:191], v[98:101]
	v_mfma_f32_16x16x32_bf16 v[98:101], v[176:179], v[192:195], v[98:101]
	v_mfma_f32_16x16x32_bf16 v[102:105], v[168:171], v[192:195], v[102:105]
	v_mfma_f32_16x16x32_bf16 v[102:105], v[158:161], v[188:191], v[102:105]
	v_mfma_f32_16x16x32_bf16 v[86:89], v[158:161], v[196:199], v[86:89]
	v_mfma_f32_16x16x32_bf16 v[86:89], v[168:171], v[200:203], v[86:89]
	v_mfma_f32_16x16x32_bf16 v[82:85], v[176:179], v[200:203], v[82:85]
	v_mfma_f32_16x16x32_bf16 v[82:85], v[172:175], v[196:199], v[82:85]
	v_mfma_f32_16x16x32_bf16 v[66:69], v[172:175], v[224:227], v[66:69]
	v_mfma_f32_16x16x32_bf16 v[66:69], v[176:179], v[228:231], v[66:69]
	v_mfma_f32_16x16x32_bf16 v[70:73], v[168:171], v[228:231], v[70:73]
	v_mfma_f32_16x16x32_bf16 v[70:73], v[158:161], v[224:227], v[70:73]
	s_setprio 0
	s_barrier
	s_add_i32 s4, s50, s31
	v_lshl_add_u64 v[204:205], v[204:205], 0, s[68:69]
	s_mov_b32 m0, s4
	ds_read_b128 v[180:183], v167 offset:49152
	ds_read_b128 v[184:187], v167 offset:50176
	ds_read_b128 v[188:191], v167 offset:51200
	ds_read_b128 v[192:195], v167 offset:52224
	ds_read_b128 v[196:199], v167 offset:53248
	ds_read_b128 v[200:203], v167 offset:54272
	ds_read_b128 v[224:227], v167 offset:55296
	ds_read_b128 v[228:231], v167 offset:56320
	global_load_lds_dwordx4 v[204:205], off
	s_add_i32 m0, s4, 0x2000
	s_add_u32 s2, s2, 0x80080
	v_lshl_add_u64 v[204:205], v[206:207], 0, s[68:69]
	s_addc_u32 s3, s3, 0
	s_add_i32 s4, s51, s31
	global_load_lds_dwordx4 v[204:205], off
	v_lshl_add_u64 v[204:205], s[2:3], 0, v[0:1]
	s_mov_b32 m0, s4
	s_nop 0
	global_load_lds_dwordx4 v[204:205], off
	v_lshl_add_u64 v[204:205], s[2:3], 0, v[134:135]
	s_add_i32 m0, s4, 0x2000
	s_nop 0
	global_load_lds_dwordx4 v[204:205], off
	v_lshl_add_u64 v[204:205], v[218:219], 0, s[68:69]
	s_mov_b32 m0, s38
	s_nop 0
	global_load_lds_dwordx4 v[204:205], off
	v_lshl_add_u64 v[204:205], v[220:221], 0, s[68:69]
	s_mov_b32 m0, s39
	s_nop 0
	global_load_lds_dwordx4 v[204:205], off
	s_waitcnt vmcnt(8)
	s_waitcnt lgkmcnt(0)
	s_barrier
	s_setprio 1
	s_waitcnt lgkmcnt(0)
	v_mfma_f32_16x16x32_bf16 v[62:65], v[142:145], v[180:183], v[62:65]
	v_mfma_f32_16x16x32_bf16 v[62:65], v[146:149], v[184:187], v[62:65]
	v_mfma_f32_16x16x32_bf16 v[58:61], v[154:157], v[184:187], v[58:61]
	v_mfma_f32_16x16x32_bf16 v[58:61], v[150:153], v[180:183], v[58:61]
	v_mfma_f32_16x16x32_bf16 v[42:45], v[150:153], v[188:191], v[42:45]
	v_mfma_f32_16x16x32_bf16 v[42:45], v[154:157], v[192:195], v[42:45]
	v_mfma_f32_16x16x32_bf16 v[46:49], v[146:149], v[192:195], v[46:49]
	v_mfma_f32_16x16x32_bf16 v[46:49], v[142:145], v[188:191], v[46:49]
	v_mfma_f32_16x16x32_bf16 v[30:33], v[142:145], v[196:199], v[30:33]
	v_mfma_f32_16x16x32_bf16 v[30:33], v[146:149], v[200:203], v[30:33]
	v_mfma_f32_16x16x32_bf16 v[26:29], v[154:157], v[200:203], v[26:29]
	v_mfma_f32_16x16x32_bf16 v[26:29], v[150:153], v[196:199], v[26:29]
	v_mfma_f32_16x16x32_bf16 v[10:13], v[150:153], v[224:227], v[10:13]
	v_mfma_f32_16x16x32_bf16 v[10:13], v[154:157], v[228:231], v[10:13]
	v_mfma_f32_16x16x32_bf16 v[14:17], v[146:149], v[228:231], v[14:17]
	v_mfma_f32_16x16x32_bf16 v[14:17], v[142:145], v[224:227], v[14:17]
	s_setprio 0
	s_setprio 1
	v_mfma_f32_16x16x32_bf16 v[54:57], v[158:161], v[180:183], v[54:57]
	v_mfma_f32_16x16x32_bf16 v[54:57], v[168:171], v[184:187], v[54:57]
	v_mfma_f32_16x16x32_bf16 v[50:53], v[176:179], v[184:187], v[50:53]
	v_mfma_f32_16x16x32_bf16 v[50:53], v[172:175], v[180:183], v[50:53]
	v_mfma_f32_16x16x32_bf16 v[34:37], v[172:175], v[188:191], v[34:37]
	v_mfma_f32_16x16x32_bf16 v[34:37], v[176:179], v[192:195], v[34:37]
	v_mfma_f32_16x16x32_bf16 v[38:41], v[168:171], v[192:195], v[38:41]
	v_mfma_f32_16x16x32_bf16 v[38:41], v[158:161], v[188:191], v[38:41]
	v_mfma_f32_16x16x32_bf16 v[22:25], v[158:161], v[196:199], v[22:25]
	v_mfma_f32_16x16x32_bf16 v[22:25], v[168:171], v[200:203], v[22:25]
	v_mfma_f32_16x16x32_bf16 v[18:21], v[176:179], v[200:203], v[18:21]
	v_mfma_f32_16x16x32_bf16 v[18:21], v[172:175], v[196:199], v[18:21]
	v_mfma_f32_16x16x32_bf16 v[2:5], v[172:175], v[224:227], v[2:5]
	v_mfma_f32_16x16x32_bf16 v[2:5], v[176:179], v[228:231], v[2:5]
	v_mfma_f32_16x16x32_bf16 v[6:9], v[168:171], v[228:231], v[6:9]
	v_mfma_f32_16x16x32_bf16 v[6:9], v[158:161], v[224:227], v[6:9]
	s_setprio 0
	s_barrier
	s_add_i32 s49, s49, 2
	s_add_u32 s0, s0, 0x100
	s_addc_u32 s1, s1, 0
	s_add_u32 s47, s47, 0x100
	s_addc_u32 s48, s48, 0
	s_cmp_gt_u32 s49, 29
	s_cbranch_scc0 .LBB0_127
	s_and_b64 vcc, exec, s[18:19]
	s_cbranch_vccz .LBB0_130
	s_barrier
